# v24 + counted vmcnt waits in the attention K/V staging: blanket vmcnt(0) after the tile barrier removed in both loop copies so each ds_write waits only for its own load
# speedup vs baseline: 1.0088x; 1.0045x over previous
; __device__ __forceinline__ void finishSM(f32x16& p0, f32x16& p1, float alpha, float& l_reg, bf16x8& pa0, bf16x8& pa1, bf16x8& pa2, bf16x8& pa3) {
; #pragma unroll
;     for (int r = 0; r < 16; ++r) p1[r] = __builtin_amdgcn_exp2f(p1[r]);
;     float ps = 0;
; #pragma unroll
;     for (int r = 0; r < 16; ++r) ps += p0[r];
; #pragma unroll
;     for (int r = 0; r < 16; ++r) ps += p1[r];
;     { auto rr = __builtin_amdgcn_permlane32_swap(__float_as_uint(ps), __float_as_uint(ps), false, false); ps = __uint_as_float(rr[0]) + __uint_as_float(rr[1]); }
;     l_reg = l_reg * alpha + ps;
; __device__ __forceinline__ void qkt(f32x16& p0, f32x16& p1, const char* Ks, const bf16x8* qr, const char* qrl, int r32, int hi) {
;     p0 = f32x16{}; p1 = f32x16{};
; #pragma unroll
;     for (int d0 = 0; d0 < 12; ++d0) { const int cb = (d0 * 16 + hi * 8) * 2;
;         const bf16x8 b0 = *reinterpret_cast<const bf16x8*>(Ks + KSWZ(r32, cb));
;         const bf16x8 b1 = *reinterpret_cast<const bf16x8*>(Ks + KSWZ(32 + r32, cb));
;         const bf16x8 qq = d0 < QREG ? qr[d0 < QREG ? d0 : 0] : *reinterpret_cast<const bf16x8*>(qrl + (d0 - QREG) * 1024);
;         p0 = __builtin_amdgcn_mfma_f32_32x32x16_bf16(b0, qq, p0, 0, 0, 0);
;         p1 = __builtin_amdgcn_mfma_f32_32x32x16_bf16(b1, qq, p1, 0, 0, 0); }
; }
.LBB0_1380:
	v_add_u32_e32 v220, s14, v183
	ds_read_b128 v[64:67], v220
	ds_read_b128 v[68:71], v220 offset:16384
	v_add_u32_e32 v221, s14, v185
	ds_read_b128 v[222:225], v221
	ds_read_b128 v[226:229], v221 offset:16384
	v_add_f32_e32 v140, 0, v136
	s_waitcnt lgkmcnt(3)
	v_mfma_f32_32x32x16_bf16 v[80:95], v[64:67], v[116:119], 0
	v_add_f32_e32 v140, v166, v140
	v_add_f32_e32 v140, v137, v140
	v_add_f32_e32 v140, v167, v140
	v_add_f32_e32 v140, v138, v140
	v_add_f32_e32 v140, v168, v140
	v_add_f32_e32 v140, v139, v140
	v_add_f32_e32 v140, v165, v140
	s_waitcnt lgkmcnt(2)
	v_mfma_f32_32x32x16_bf16 v[64:79], v[68:71], v[116:119], 0
	v_add_f32_e32 v140, v144, v140
	v_add_f32_e32 v140, v146, v140
	v_add_f32_e32 v140, v145, v140
	v_add_f32_e32 v140, v164, v140
	v_exp_f32_e32 v132, v132
	v_add_f32_e32 v140, v141, v140
	v_exp_f32_e32 v133, v133
	s_waitcnt lgkmcnt(1)
	v_mfma_f32_32x32x16_bf16 v[80:95], v[222:225], v[112:115], v[80:95]
	v_add_u32_e32 v222, s14, v187
	v_add_u32_e32 v223, s14, v189
	v_add_f32_e32 v140, v143, v140
	v_exp_f32_e32 v134, v134
	v_add_f32_e32 v140, v142, v140
	v_exp_f32_e32 v135, v135
	v_add_f32_e32 v140, v147, v140
	s_waitcnt lgkmcnt(0)
	v_mfma_f32_32x32x16_bf16 v[64:79], v[226:229], v[112:115], v[64:79]
	ds_read_b128 v[224:227], v222
	ds_read_b128 v[228:231], v222 offset:16384
	v_exp_f32_e32 v122, v122
	v_add_f32_e32 v140, v132, v140
	v_exp_f32_e32 v123, v123
	v_add_f32_e32 v140, v133, v140
	v_exp_f32_e32 v124, v124
	v_add_f32_e32 v140, v134, v140
	s_waitcnt lgkmcnt(1)
	v_mfma_f32_32x32x16_bf16 v[80:95], v[224:227], v[108:111], v[80:95]
	v_exp_f32_e32 v125, v125
	v_add_f32_e32 v140, v135, v140
	v_exp_f32_e32 v126, v126
	v_add_f32_e32 v140, v122, v140
	v_exp_f32_e32 v127, v127
	v_add_f32_e32 v140, v123, v140
	v_exp_f32_e32 v130, v130
	s_waitcnt lgkmcnt(0)
	v_mfma_f32_32x32x16_bf16 v[64:79], v[228:231], v[108:111], v[64:79]
	ds_read_b128 v[224:227], v223
	ds_read_b128 v[228:231], v223 offset:16384
	v_add_f32_e32 v140, v124, v140
	v_exp_f32_e32 v131, v131
	v_add_f32_e32 v140, v125, v140
	v_exp_f32_e32 v120, v120
	v_add_f32_e32 v140, v126, v140
	v_exp_f32_e32 v121, v121
	s_waitcnt lgkmcnt(1)
	v_mfma_f32_32x32x16_bf16 v[80:95], v[224:227], v[104:107], v[80:95]
	v_add_u32_e32 v224, s14, v191
	v_add_u32_e32 v225, s14, v193
	v_add_f32_e32 v140, v127, v140
	v_exp_f32_e32 v128, v128
	v_add_f32_e32 v140, v130, v140
	v_exp_f32_e32 v129, v129
	v_add_f32_e32 v140, v131, v140
	s_waitcnt lgkmcnt(0)
	v_mfma_f32_32x32x16_bf16 v[64:79], v[228:231], v[104:107], v[64:79]
	ds_read_b128 v[226:229], v224
	ds_read_b128 v[230:233], v224 offset:16384
	v_add_f32_e32 v140, v120, v140
	v_add_f32_e32 v140, v121, v140
	v_add_f32_e32 v140, v128, v140
	s_waitcnt lgkmcnt(1)
	v_mfma_f32_32x32x16_bf16 v[80:95], v[226:229], v[100:103], v[80:95]
	s_waitcnt lgkmcnt(0)
	v_mfma_f32_32x32x16_bf16 v[64:79], v[230:233], v[100:103], v[64:79]
	ds_read_b128 v[226:229], v225
	ds_read_b128 v[230:233], v225 offset:16384
	s_waitcnt lgkmcnt(1)
	v_mfma_f32_32x32x16_bf16 v[80:95], v[226:229], v[96:99], v[80:95]
	v_add_u32_e32 v226, s14, v195
	v_add_u32_e32 v227, s14, v197
	s_waitcnt lgkmcnt(0)
	v_mfma_f32_32x32x16_bf16 v[64:79], v[230:233], v[96:99], v[64:79]
	ds_read_b128 v[228:231], v226
	ds_read_b128 v[232:235], v226 offset:16384
	ds_read_b128 v[236:239], v177
	s_waitcnt lgkmcnt(0)
	v_mfma_f32_32x32x16_bf16 v[80:95], v[228:231], v[236:239], v[80:95]
	v_mfma_f32_32x32x16_bf16 v[64:79], v[232:235], v[236:239], v[64:79]
	ds_read_b128 v[228:231], v227
	ds_read_b128 v[232:235], v227 offset:16384
	ds_read_b128 v[236:239], v177 offset:1024
	s_waitcnt lgkmcnt(0)
	v_mfma_f32_32x32x16_bf16 v[80:95], v[228:231], v[236:239], v[80:95]
	v_add_u32_e32 v229, s14, v199
	v_add_u32_e32 v228, s14, v201
	v_mfma_f32_32x32x16_bf16 v[64:79], v[232:235], v[236:239], v[64:79]
	ds_read_b128 v[230:233], v229
	ds_read_b128 v[234:237], v229 offset:16384
	ds_read_b128 v[238:241], v177 offset:2048
	s_waitcnt lgkmcnt(0)
	v_mfma_f32_32x32x16_bf16 v[80:95], v[230:233], v[238:241], v[80:95]
	v_mfma_f32_32x32x16_bf16 v[64:79], v[234:237], v[238:241], v[64:79]
	ds_read_b128 v[230:233], v228
	ds_read_b128 v[234:237], v228 offset:16384
	ds_read_b128 v[238:241], v177 offset:3072
	s_waitcnt lgkmcnt(0)
	v_mfma_f32_32x32x16_bf16 v[80:95], v[230:233], v[238:241], v[80:95]
	v_add_u32_e32 v230, s14, v203
	v_add_u32_e32 v231, s14, v205
	v_mfma_f32_32x32x16_bf16 v[64:79], v[234:237], v[238:241], v[64:79]
	ds_read_b128 v[232:235], v230
	ds_read_b128 v[236:239], v230 offset:16384
	ds_read_b128 v[240:243], v177 offset:4096
	s_waitcnt lgkmcnt(0)
	v_mfma_f32_32x32x16_bf16 v[80:95], v[232:235], v[240:243], v[80:95]
	v_mfma_f32_32x32x16_bf16 v[64:79], v[236:239], v[240:243], v[64:79]
	ds_read_b128 v[232:235], v231
	ds_read_b128 v[236:239], v231 offset:16384
	ds_read_b128 v[240:243], v177 offset:5120
	v_cvt_pk_bf16_f32 v136, v136, v166
	v_cvt_pk_bf16_f32 v137, v137, v167
	v_cvt_pk_bf16_f32 v138, v138, v168
	v_cvt_pk_bf16_f32 v139, v139, v165
	v_cvt_pk_bf16_f32 v144, v144, v146
	v_cvt_pk_bf16_f32 v145, v145, v164
	s_waitcnt lgkmcnt(0)
; #define SBAR() __builtin_amdgcn_sched_barrier(0)
; template <int OFF> __device__ __forceinline__ s16x4 tr_read(int vb) { s16x4 r; asm volatile("ds_read_b64_tr_b16 %0, %1 offset:%2" : "=&v"(r) : "v"(vb), "i"(OFF) : "memory"); return r; }
; __device__ __forceinline__ void partialSM(f32x16& p0, f32x16& p1, float& m_reg, float& mn, float& alpha) {
;     float pmax = p0[0];
; #pragma unroll
;     for (int r = 1; r < 16; ++r) pmax = fmaxf(pmax, p0[r]);
; #pragma unroll
;     for (int r = 0; r < 16; ++r) pmax = fmaxf(pmax, p1[r]);
;     { auto rr = __builtin_amdgcn_permlane32_swap(__float_as_uint(pmax), __float_as_uint(pmax), false, false); pmax = fmaxf(__uint_as_float(rr[0]), __uint_as_float(rr[1])); }
;     if (__builtin_expect(__all(pmax - m_reg <= THR2), 1)) { mn = m_reg; alpha = 1.f; }
;     else { mn = fmaxf(m_reg, pmax); alpha = __builtin_amdgcn_exp2f(m_reg - mn); m_reg = mn; }
; template <int D0> __device__ __forceinline__ void pv_one(f32x16& od, int vb, bf16x8 pa0, bf16x8 pa1, bf16x8 pa2, bf16x8 pa3) {
;     const s16x4 l0 = tr_read<v_rd_off(D0, 0, 0)>(vb), h0 = tr_read<v_rd_off(D0, 0, 1)>(vb), l1 = tr_read<v_rd_off(D0, 1, 0)>(vb), h1 = tr_read<v_rd_off(D0, 1, 1)>(vb);
;     const s16x4 l2 = tr_read<v_rd_off(D0, 2, 0)>(vb), h2 = tr_read<v_rd_off(D0, 2, 1)>(vb), l3 = tr_read<v_rd_off(D0, 3, 0)>(vb), h3 = tr_read<v_rd_off(D0, 3, 1)>(vb);
;     asm volatile("s_waitcnt lgkmcnt(0)" ::: "memory"); SBAR();
;     ...
;     od = __builtin_amdgcn_mfma_f32_32x32x16_bf16(pa0, PK(l0, h0), od, 0, 0, 0);
;     od = __builtin_amdgcn_mfma_f32_32x32x16_bf16(pa1, PK(l1, h1), od, 0, 0, 0);
;     od = __builtin_amdgcn_mfma_f32_32x32x16_bf16(pa2, PK(l2, h2), od, 0, 0, 0);
;     od = __builtin_amdgcn_mfma_f32_32x32x16_bf16(pa3, PK(l3, h3), od, 0, 0, 0);
;     ...
; }
; __device__ __forceinline__ void pv_d0(f32x16* o, int vb, bf16x8 pa0, bf16x8 pa1, bf16x8 pa2, bf16x8 pa3) {
;     pv_one<0>(o[0], vb, pa0, pa1, pa2, pa3); pv_one<1>(o[1], vb, pa0, pa1, pa2, pa3); pv_one<2>(o[2], vb, pa0, pa1, pa2, pa3); pv_one<3>(o[3], vb, pa0, pa1, pa2, pa3);
; }
	v_mfma_f32_32x32x16_bf16 v[80:95], v[232:235], v[240:243], v[80:95]
	v_add_f32_e32 v232, v129, v140
	v_mov_b32_e32 v233, v232
	v_cvt_pk_bf16_f32 v146, v141, v143
	v_cvt_pk_bf16_f32 v147, v142, v147
	v_cvt_pk_bf16_f32 v234, v132, v133
	v_cvt_pk_bf16_f32 v235, v134, v135
	s_nop 1
	v_permlane32_swap_b32_e32 v232, v233
	v_mfma_f32_32x32x16_bf16 v[64:79], v[236:239], v[240:243], v[64:79]
	v_cvt_pk_bf16_f32 v236, v122, v123
	v_permlane32_swap_b32_e32 v136, v138
	v_cvt_pk_bf16_f32 v237, v124, v125
	v_permlane32_swap_b32_e32 v234, v236
	v_cvt_pk_bf16_f32 v238, v126, v127
	v_cvt_pk_bf16_f32 v239, v130, v131
	v_cvt_pk_bf16_f32 v240, v120, v121
	v_cvt_pk_bf16_f32 v241, v128, v129
	v_permlane32_swap_b32_e32 v137, v139
	v_permlane32_swap_b32_e32 v144, v146
	v_permlane32_swap_b32_e32 v145, v147
	v_permlane32_swap_b32_e32 v235, v237
	v_permlane32_swap_b32_e32 v238, v240
	v_permlane32_swap_b32_e32 v239, v241
	v_lshl_add_u64 v[164:165], s[68:69], 0, v[156:157]
	s_mov_b32 s4, 0x23480000
	v_add_co_u32_e32 v120, vcc, s4, v164
	s_mov_b32 s4, 0x234a0000
	s_nop 0
	v_addc_co_u32_e32 v121, vcc, 0, v165, vcc
	v_add_co_u32_e32 v124, vcc, s4, v164
	v_lshl_add_u64 v[166:167], s[68:69], 0, v[154:155]
	s_nop 0
	v_addc_co_u32_e32 v125, vcc, 0, v165, vcc
	v_add_co_u32_e32 v128, vcc, s97, v166
	v_lshl_add_u64 v[168:169], s[68:69], 0, v[152:153]
	s_nop 0
	v_addc_co_u32_e32 v129, vcc, 0, v167, vcc
	v_add_co_u32_e32 v132, vcc, s97, v168
	v_lshl_add_u64 v[170:171], s[68:69], 0, v[150:151]
	s_nop 0
	v_addc_co_u32_e32 v133, vcc, 0, v169, vcc
	v_add_co_u32_e32 v140, vcc, s97, v170
	global_load_dwordx4 v[120:123], v[120:121], off
	s_nop 0
	global_load_dwordx4 v[124:127], v[124:125], off
	s_nop 0
	global_load_dwordx4 v[128:131], v[128:129], off
	s_nop 0
	global_load_dwordx4 v[132:135], v[132:133], off
	v_addc_co_u32_e32 v141, vcc, 0, v171, vcc
	global_load_dwordx4 v[140:143], v[140:141], off
	ds_read_b64_tr_b16 v[242:243], v176 offset:0
	ds_read_b64_tr_b16 v[244:245], v176 offset:0x800
	ds_read_b64_tr_b16 v[246:247], v176 offset:0x1000
	ds_read_b64_tr_b16 v[248:249], v176 offset:0x1800
	ds_read_b64_tr_b16 v[250:251], v176 offset:0x2000
	ds_read_b64_tr_b16 v[252:253], v176 offset:0x2800
	ds_read_b64_tr_b16 v[208:209], v176 offset:0x3000
	ds_read_b64_tr_b16 v[210:211], v176 offset:0x3800
	s_waitcnt lgkmcnt(0)
	s_nop 0
	v_mfma_f32_32x32x16_bf16 v[0:15], v[136:139], v[242:245], v[0:15]
	v_mfma_f32_32x32x16_bf16 v[0:15], v[144:147], v[246:249], v[0:15]
	v_mfma_f32_32x32x16_bf16 v[0:15], v[234:237], v[250:253], v[0:15]
	v_mfma_f32_32x32x16_bf16 v[0:15], v[238:241], v[208:211], v[0:15]
	ds_read_b64_tr_b16 v[208:209], v176 offset:0x200
	ds_read_b64_tr_b16 v[210:211], v176 offset:0xa00
	ds_read_b64_tr_b16 v[242:243], v176 offset:0x1200
	ds_read_b64_tr_b16 v[244:245], v176 offset:0x1a00
	ds_read_b64_tr_b16 v[246:247], v176 offset:0x2200
	ds_read_b64_tr_b16 v[248:249], v176 offset:0x2a00
	ds_read_b64_tr_b16 v[250:251], v176 offset:0x3200
	ds_read_b64_tr_b16 v[252:253], v176 offset:0x3a00
	s_waitcnt lgkmcnt(0)
	s_nop 0
	v_mfma_f32_32x32x16_bf16 v[48:63], v[136:139], v[208:211], v[48:63]
	ds_read_b64_tr_b16 v[208:209], v176 offset:0x400
	ds_read_b64_tr_b16 v[210:211], v176 offset:0xc00
	v_mfma_f32_32x32x16_bf16 v[48:63], v[144:147], v[242:245], v[48:63]
	ds_read_b64_tr_b16 v[242:243], v176 offset:0x1400
	ds_read_b64_tr_b16 v[244:245], v176 offset:0x1c00
	v_mfma_f32_32x32x16_bf16 v[48:63], v[234:237], v[246:249], v[48:63]
	ds_read_b64_tr_b16 v[246:247], v176 offset:0x2400
	ds_read_b64_tr_b16 v[248:249], v176 offset:0x2c00
	v_mfma_f32_32x32x16_bf16 v[48:63], v[238:241], v[250:253], v[48:63]
	ds_read_b64_tr_b16 v[250:251], v176 offset:0x3400
	ds_read_b64_tr_b16 v[252:253], v176 offset:0x3c00
	s_waitcnt lgkmcnt(0)
	v_mfma_f32_32x32x16_bf16 v[32:47], v[136:139], v[208:211], v[32:47]
	ds_read_b64_tr_b16 v[208:209], v176 offset:0x600
	ds_read_b64_tr_b16 v[210:211], v176 offset:0xe00
	v_mfma_f32_32x32x16_bf16 v[32:47], v[144:147], v[242:245], v[32:47]
	ds_read_b64_tr_b16 v[242:243], v176 offset:0x1600
	ds_read_b64_tr_b16 v[244:245], v176 offset:0x1e00
	v_mfma_f32_32x32x16_bf16 v[32:47], v[234:237], v[246:249], v[32:47]
	ds_read_b64_tr_b16 v[246:247], v176 offset:0x2600
	ds_read_b64_tr_b16 v[248:249], v176 offset:0x2e00
	v_mfma_f32_32x32x16_bf16 v[32:47], v[238:241], v[250:253], v[32:47]
	ds_read_b64_tr_b16 v[250:251], v176 offset:0x3600
	ds_read_b64_tr_b16 v[252:253], v176 offset:0x3e00
	s_waitcnt lgkmcnt(0)
	v_mfma_f32_32x32x16_bf16 v[16:31], v[136:139], v[208:211], v[16:31]
	v_max_f32_e32 v136, v81, v81
	v_max_f32_e32 v137, v80, v80
	v_max_f32_e32 v136, v137, v136
	v_max3_f32 v136, v136, v82, v83
	v_max3_f32 v136, v136, v84, v85
	v_max3_f32 v136, v136, v86, v87
	v_max3_f32 v136, v136, v88, v89
	v_max3_f32 v136, v136, v90, v91
	v_mfma_f32_32x32x16_bf16 v[16:31], v[144:147], v[242:245], v[16:31]
	v_max3_f32 v136, v136, v92, v93
	v_max3_f32 v136, v136, v94, v95
	v_max3_f32 v136, v136, v64, v65
	v_max3_f32 v136, v136, v66, v67
	v_max3_f32 v136, v136, v68, v69
	v_max3_f32 v136, v136, v70, v71
	v_max3_f32 v136, v136, v72, v73
	v_max3_f32 v136, v136, v74, v75
	v_mfma_f32_32x32x16_bf16 v[16:31], v[234:237], v[246:249], v[16:31]
	v_max3_f32 v136, v136, v76, v77
	v_max3_f32 v136, v136, v78, v79
	v_mov_b32_e32 v137, v136
	s_nop 1
	v_permlane32_swap_b32_e32 v136, v137
	v_max_f32_e32 v137, v137, v137
	v_max_f32_e32 v136, v136, v136
	v_max_f32_e32 v136, v136, v137
	v_sub_f32_e32 v137, v136, v158
	v_cmp_ge_f32_e32 vcc, s62, v137
	v_max_f32_e32 v137, v158, v158
	v_mfma_f32_32x32x16_bf16 v[16:31], v[238:241], v[250:253], v[16:31]
	v_max_f32_e32 v136, v137, v136
	v_sub_f32_e32 v137, v158, v136
	v_exp_f32_e32 v137, v137
	s_cmp_eq_u64 vcc, exec
	s_cselect_b64 s[4:5], -1, 0
	s_barrier
; #define SBAR() __builtin_amdgcn_sched_barrier(0)
; #define SWRITE(b) do { *(bf16x8*)(V_lds + (b) * SHM_V + vst0) = vs0; *(bf16x8*)(V_lds + (b) * SHM_V + vst1) = vs1; \
;     *(bf16x8*)(K_lds + (b) * SHM_K + KSWZ(kr0, kc0 * 16)) = ks0; *(bf16x8*)(K_lds + (b) * SHM_K + KSWZ(kr1, kc1 * 16)) = ks1; *(bf16x8*)(K_lds + (b) * SHM_K + KSWZ(kr2, kc2 * 16)) = ks2; } while (0)
; #define SWAIT() asm volatile("s_waitcnt vmcnt(0)" ::: "memory")
; #define RESC(a) do { if (__any((a) < 1.f)) { if (hi == 0) al_l[r32] = (a); asm volatile("s_waitcnt lgkmcnt(0)" ::: "memory"); \
;     _Pragma("unroll") for (int d = 0; d < 4; ++d) _Pragma("unroll") for (int r = 0; r < 16; ++r) o[d][r] *= al_l[crow(r, hi)]; } } while (0)
; __device__ __forceinline__ void partialSM(f32x16& p0, f32x16& p1, float& m_reg, float& mn, float& alpha) {
;     ...
;     for (int r = 0; r < 16; ++r) p0[r] = p0[r] - mn;
; #pragma unroll
;     for (int r = 0; r < 16; ++r) p1[r] = p1[r] - mn;
; #pragma unroll
;     for (int r = 0; r < 16; ++r) p0[r] = __builtin_amdgcn_exp2f(p0[r]);
; __device__ __forceinline__ void attn_unit(const bf16_t* __restrict__ Qb, const bf16_t* __restrict__ Kh, const bf16_t* __restrict__ Vh, bf16_t* __restrict__ Ob, int seq, char* lds) {
;     ...
;     f32x16 pA0, pA1, pB0, pB1; float mnA, mnB, alA, alB; bf16x8 pa0, pa1, pa2, pa3; const int NT = seq / KVBLK;
;     SLOAD(0); SWAIT(); SWRITE(0); __syncthreads();
;     qkt(pA0, pA1, K_lds, qr, qrl, r32, hi); partialSM(pA0, pA1, m_reg, mnA, alA);
;     SLOAD(KVBLK);
;     SWAIT(); SWRITE(1); __syncthreads();
;     for (int j = 1; j + 1 < NT; j += 2) {
;         SBAR(); qkt(pB0, pB1, K_lds + SHM_K, qr, qrl, r32, hi);
;         finishSM(pA0, pA1, alA, l_reg, pa0, pa1, pa2, pa3); SBAR();
;         SLOAD((j + 1) * KVBLK); SBAR();
;         pv_d0(o, vb0, pa0, pa1, pa2, pa3); partialSM(pB0, pB1, m_reg, mnB, alB);
;         __syncthreads(); SWAIT(); SWRITE(0);
;         RESC(alB); __syncthreads();
;         SBAR(); qkt(pA0, pA1, K_lds, qr, qrl, r32, hi);
	v_cndmask_b32_e64 v234, v137, 1.0, s[4:5]
	v_cmp_gt_f32_e32 vcc, 1.0, v234
	s_waitcnt vmcnt(4)
	ds_write_b128 v178, v[120:123]
	s_waitcnt vmcnt(3)
	ds_write_b128 v179, v[124:127]
	s_waitcnt vmcnt(2)
	ds_write_b128 v180, v[128:131] offset:32768
	s_waitcnt vmcnt(1)
	ds_write_b128 v181, v[132:135] offset:32768
	s_waitcnt vmcnt(0)
	ds_write_b128 v182, v[140:143] offset:32768
	s_cbranch_vccz .LBB0_1384
	s_and_saveexec_b64 s[12:13], s[2:3]
	ds_write_b32 v173, v234 offset:128
	s_or_b64 exec, exec, s[12:13]
	s_waitcnt lgkmcnt(0)
	v_add_u32_e32 v132, v149, v160
	ds_read_b128 v[120:123], v132 offset:224
	ds_read_b128 v[124:127], v132 offset:192
	ds_read_b128 v[128:131], v132 offset:160
	ds_read_b128 v[132:135], v132 offset:128
	s_waitcnt lgkmcnt(3)
	v_pk_mul_f32 v[12:13], v[12:13], v[120:121]
	s_waitcnt lgkmcnt(2)
	v_pk_mul_f32 v[8:9], v[8:9], v[124:125]
	s_waitcnt lgkmcnt(1)
	v_pk_mul_f32 v[4:5], v[4:5], v[128:129]
	v_pk_mul_f32 v[14:15], v[14:15], v[122:123]
	v_pk_mul_f32 v[10:11], v[10:11], v[126:127]
	v_pk_mul_f32 v[6:7], v[6:7], v[130:131]
	s_waitcnt lgkmcnt(0)
	v_pk_mul_f32 v[2:3], v[2:3], v[134:135]
	v_pk_mul_f32 v[0:1], v[0:1], v[132:133]
	v_pk_mul_f32 v[60:61], v[60:61], v[120:121]
	v_pk_mul_f32 v[56:57], v[56:57], v[124:125]
	v_pk_mul_f32 v[52:53], v[52:53], v[128:129]
	v_pk_mul_f32 v[62:63], v[62:63], v[122:123]
	v_pk_mul_f32 v[58:59], v[58:59], v[126:127]
	v_pk_mul_f32 v[54:55], v[54:55], v[130:131]
	v_pk_mul_f32 v[50:51], v[50:51], v[134:135]
	v_pk_mul_f32 v[48:49], v[48:49], v[132:133]
	v_pk_mul_f32 v[44:45], v[44:45], v[120:121]
	v_pk_mul_f32 v[40:41], v[40:41], v[124:125]
	v_pk_mul_f32 v[36:37], v[36:37], v[128:129]
	v_pk_mul_f32 v[46:47], v[46:47], v[122:123]
	v_pk_mul_f32 v[42:43], v[42:43], v[126:127]
	v_pk_mul_f32 v[38:39], v[38:39], v[130:131]
	v_pk_mul_f32 v[34:35], v[34:35], v[134:135]
	v_pk_mul_f32 v[32:33], v[32:33], v[132:133]
	v_pk_mul_f32 v[28:29], v[28:29], v[120:121]
	v_pk_mul_f32 v[24:25], v[24:25], v[124:125]
	v_pk_mul_f32 v[20:21], v[20:21], v[128:129]
	v_pk_mul_f32 v[30:31], v[30:31], v[122:123]
	v_pk_mul_f32 v[26:27], v[26:27], v[126:127]
	v_pk_mul_f32 v[22:23], v[22:23], v[130:131]
	v_pk_mul_f32 v[18:19], v[18:19], v[134:135]
	v_pk_mul_f32 v[16:17], v[16:17], v[132:133]
.LBB0_1384:
	v_cndmask_b32_e64 v158, v136, v158, s[4:5]
	v_sub_f32_e32 v80, v80, v158
	v_sub_f32_e32 v81, v81, v158
	v_sub_f32_e32 v82, v82, v158
	v_sub_f32_e32 v83, v83, v158
	v_sub_f32_e32 v84, v84, v158
	v_sub_f32_e32 v85, v85, v158
	v_sub_f32_e32 v86, v86, v158
	v_sub_f32_e32 v87, v87, v158
	v_sub_f32_e32 v88, v88, v158
	v_sub_f32_e32 v89, v89, v158
	v_sub_f32_e32 v90, v90, v158
	v_sub_f32_e32 v91, v91, v158
	v_sub_f32_e32 v92, v92, v158
	v_sub_f32_e32 v93, v93, v158
	v_sub_f32_e32 v94, v94, v158
	v_sub_f32_e32 v95, v95, v158
	v_sub_f32_e32 v235, v68, v158
	v_sub_f32_e32 v236, v69, v158
	v_exp_f32_e32 v133, v80
	v_exp_f32_e32 v135, v81
	v_exp_f32_e32 v131, v82
	v_exp_f32_e32 v134, v83
	v_exp_f32_e32 v130, v84
	v_exp_f32_e32 v132, v85
	v_exp_f32_e32 v128, v86
	v_exp_f32_e32 v129, v87
	v_exp_f32_e32 v125, v88
	v_exp_f32_e32 v127, v89
	v_exp_f32_e32 v124, v90
	v_exp_f32_e32 v126, v91
	v_exp_f32_e32 v121, v92
	v_exp_f32_e32 v123, v93
	v_exp_f32_e32 v120, v94
	v_exp_f32_e32 v122, v95
	v_sub_f32_e32 v208, v64, v158
	v_sub_f32_e32 v209, v65, v158
	v_sub_f32_e32 v210, v66, v158
	v_sub_f32_e32 v211, v67, v158
	v_sub_f32_e32 v237, v70, v158
	v_sub_f32_e32 v238, v71, v158
	v_sub_f32_e32 v239, v72, v158
	v_sub_f32_e32 v240, v73, v158
	v_sub_f32_e32 v241, v74, v158
	v_sub_f32_e32 v242, v75, v158
	v_sub_f32_e32 v243, v76, v158
	v_sub_f32_e32 v244, v77, v158
	v_sub_f32_e32 v245, v78, v158
	v_sub_f32_e32 v246, v79, v158
	s_waitcnt lgkmcnt(0)
	s_barrier
	ds_read_b128 v[64:67], v184 offset:32768
	ds_read_b128 v[68:71], v184 offset:49152
	ds_read_b128 v[136:139], v186 offset:32768
	ds_read_b128 v[140:143], v186 offset:49152
	v_exp_f32_e32 v237, v237
	v_exp_f32_e32 v238, v238
	s_waitcnt lgkmcnt(3)
	v_mfma_f32_32x32x16_bf16 v[80:95], v[64:67], v[116:119], 0
	v_exp_f32_e32 v239, v239
	v_exp_f32_e32 v240, v240
	v_exp_f32_e32 v241, v241
	v_exp_f32_e32 v242, v242
	v_exp_f32_e32 v243, v243
	v_exp_f32_e32 v244, v244
	v_exp_f32_e32 v245, v245
	s_waitcnt lgkmcnt(2)
	v_mfma_f32_32x32x16_bf16 v[64:79], v[68:71], v[116:119], 0
	v_exp_f32_e32 v246, v246
	ds_read_b128 v[220:223], v188 offset:32768
	ds_read_b128 v[224:227], v188 offset:49152
	s_waitcnt lgkmcnt(2)
	v_mfma_f32_32x32x16_bf16 v[64:79], v[140:143], v[112:115], v[64:79]
	v_mfma_f32_32x32x16_bf16 v[80:95], v[136:139], v[112:115], v[80:95]
	ds_read_b128 v[136:139], v190 offset:32768
	ds_read_b128 v[140:143], v190 offset:49152
	s_waitcnt lgkmcnt(2)
	v_mfma_f32_32x32x16_bf16 v[64:79], v[224:227], v[108:111], v[64:79]
	v_mfma_f32_32x32x16_bf16 v[80:95], v[220:223], v[108:111], v[80:95]
	ds_read_b128 v[220:223], v192 offset:32768
	ds_read_b128 v[224:227], v192 offset:49152
	s_waitcnt lgkmcnt(2)
	v_mfma_f32_32x32x16_bf16 v[64:79], v[140:143], v[104:107], v[64:79]
	v_mfma_f32_32x32x16_bf16 v[80:95], v[136:139], v[104:107], v[80:95]
	ds_read_b128 v[136:139], v194 offset:32768
	ds_read_b128 v[140:143], v194 offset:49152
	s_waitcnt lgkmcnt(2)
	v_mfma_f32_32x32x16_bf16 v[64:79], v[224:227], v[100:103], v[64:79]
	v_mfma_f32_32x32x16_bf16 v[80:95], v[220:223], v[100:103], v[80:95]
	ds_read_b128 v[220:223], v196 offset:32768
	ds_read_b128 v[224:227], v196 offset:49152
	ds_read_b128 v[228:231], v177
	s_waitcnt lgkmcnt(3)
	v_mfma_f32_32x32x16_bf16 v[64:79], v[140:143], v[96:99], v[64:79]
	v_mfma_f32_32x32x16_bf16 v[80:95], v[136:139], v[96:99], v[80:95]
	ds_read_b128 v[136:139], v198 offset:32768
	ds_read_b128 v[140:143], v198 offset:49152
	ds_read_b128 v[144:147], v177 offset:1024
	s_waitcnt lgkmcnt(3)
; #define SBAR() __builtin_amdgcn_sched_barrier(0)
; template <int OFF> __device__ __forceinline__ s16x4 tr_read(int vb) { s16x4 r; asm volatile("ds_read_b64_tr_b16 %0, %1 offset:%2" : "=&v"(r) : "v"(vb), "i"(OFF) : "memory"); return r; }
; __device__ __forceinline__ void finishSM(f32x16& p0, f32x16& p1, float alpha, float& l_reg, bf16x8& pa0, bf16x8& pa1, bf16x8& pa2, bf16x8& pa3) {
; #pragma unroll
;     for (int r = 0; r < 16; ++r) p1[r] = __builtin_amdgcn_exp2f(p1[r]);
;     float ps = 0;
; #pragma unroll
;     for (int r = 0; r < 16; ++r) ps += p0[r];
; #pragma unroll
;     for (int r = 0; r < 16; ++r) ps += p1[r];
;     { auto rr = __builtin_amdgcn_permlane32_swap(__float_as_uint(ps), __float_as_uint(ps), false, false); ps = __uint_as_float(rr[0]) + __uint_as_float(rr[1]); }
;     l_reg = l_reg * alpha + ps;
;     ...
;     PK4(p0, 0, pa0); PK4(p0, 8, pa1); PK4(p1, 0, pa2); PK4(p1, 8, pa3);
; template <int D0> __device__ __forceinline__ void pv_one(f32x16& od, int vb, bf16x8 pa0, bf16x8 pa1, bf16x8 pa2, bf16x8 pa3) {
;     const s16x4 l0 = tr_read<v_rd_off(D0, 0, 0)>(vb), h0 = tr_read<v_rd_off(D0, 0, 1)>(vb), l1 = tr_read<v_rd_off(D0, 1, 0)>(vb), h1 = tr_read<v_rd_off(D0, 1, 1)>(vb);
;     const s16x4 l2 = tr_read<v_rd_off(D0, 2, 0)>(vb), h2 = tr_read<v_rd_off(D0, 2, 1)>(vb), l3 = tr_read<v_rd_off(D0, 3, 0)>(vb), h3 = tr_read<v_rd_off(D0, 3, 1)>(vb);
;     asm volatile("s_waitcnt lgkmcnt(0)" ::: "memory"); SBAR();
;     ...
;     od = __builtin_amdgcn_mfma_f32_32x32x16_bf16(pa0, PK(l0, h0), od, 0, 0, 0);
;     od = __builtin_amdgcn_mfma_f32_32x32x16_bf16(pa1, PK(l1, h1), od, 0, 0, 0);
;     od = __builtin_amdgcn_mfma_f32_32x32x16_bf16(pa2, PK(l2, h2), od, 0, 0, 0);
;     od = __builtin_amdgcn_mfma_f32_32x32x16_bf16(pa3, PK(l3, h3), od, 0, 0, 0);
;     ...
; }
; __device__ __forceinline__ void pv_d0(f32x16* o, int vb, bf16x8 pa0, bf16x8 pa1, bf16x8 pa2, bf16x8 pa3) {
;     pv_one<0>(o[0], vb, pa0, pa1, pa2, pa3); pv_one<1>(o[1], vb, pa0, pa1, pa2, pa3); pv_one<2>(o[2], vb, pa0, pa1, pa2, pa3); pv_one<3>(o[3], vb, pa0, pa1, pa2, pa3);
; }
	v_mfma_f32_32x32x16_bf16 v[64:79], v[224:227], v[228:231], v[64:79]
	v_mfma_f32_32x32x16_bf16 v[80:95], v[220:223], v[228:231], v[80:95]
	ds_read_b128 v[220:223], v200 offset:32768
	ds_read_b128 v[224:227], v200 offset:49152
	ds_read_b128 v[228:231], v177 offset:2048
	s_waitcnt lgkmcnt(3)
	v_mfma_f32_32x32x16_bf16 v[64:79], v[140:143], v[144:147], v[64:79]
	v_mfma_f32_32x32x16_bf16 v[80:95], v[136:139], v[144:147], v[80:95]
	ds_read_b128 v[136:139], v202 offset:32768
	ds_read_b128 v[140:143], v202 offset:49152
	ds_read_b128 v[144:147], v177 offset:3072
	s_waitcnt lgkmcnt(3)
	v_mfma_f32_32x32x16_bf16 v[64:79], v[224:227], v[228:231], v[64:79]
	v_mfma_f32_32x32x16_bf16 v[80:95], v[220:223], v[228:231], v[80:95]
	ds_read_b128 v[220:223], v204 offset:32768
	ds_read_b128 v[224:227], v204 offset:49152
	ds_read_b128 v[228:231], v177 offset:4096
	s_waitcnt lgkmcnt(3)
	v_mfma_f32_32x32x16_bf16 v[64:79], v[140:143], v[144:147], v[64:79]
	v_mfma_f32_32x32x16_bf16 v[80:95], v[136:139], v[144:147], v[80:95]
	ds_read_b128 v[136:139], v215 offset:32768
	ds_read_b128 v[140:143], v215 offset:49152
	ds_read_b128 v[144:147], v177 offset:5120
	s_waitcnt lgkmcnt(3)
	v_mfma_f32_32x32x16_bf16 v[64:79], v[224:227], v[228:231], v[64:79]
	v_mfma_f32_32x32x16_bf16 v[80:95], v[220:223], v[228:231], v[80:95]
	s_waitcnt lgkmcnt(0)
	v_mfma_f32_32x32x16_bf16 v[64:79], v[140:143], v[144:147], v[64:79]
	v_add_f32_e32 v140, 0, v133
	v_add_f32_e32 v140, v135, v140
	v_add_f32_e32 v140, v131, v140
	v_add_f32_e32 v140, v134, v140
	v_add_f32_e32 v140, v130, v140
	v_add_f32_e32 v140, v132, v140
	v_add_f32_e32 v140, v128, v140
	v_add_f32_e32 v140, v129, v140
	v_add_f32_e32 v140, v125, v140
	v_add_f32_e32 v140, v127, v140
	v_add_f32_e32 v140, v124, v140
	v_add_f32_e32 v140, v126, v140
	v_mfma_f32_32x32x16_bf16 v[80:95], v[136:139], v[144:147], v[80:95]
	v_exp_f32_e32 v136, v208
	v_add_f32_e32 v140, v121, v140
	v_exp_f32_e32 v137, v209
	v_add_f32_e32 v140, v123, v140
	v_exp_f32_e32 v138, v210
	v_add_f32_e32 v140, v120, v140
	v_exp_f32_e32 v139, v211
	v_add_f32_e32 v140, v122, v140
	v_exp_f32_e32 v210, v235
	v_add_f32_e32 v140, v136, v140
	v_exp_f32_e32 v211, v236
	v_add_f32_e32 v140, v137, v140
	v_add_f32_e32 v140, v138, v140
	v_add_f32_e32 v140, v139, v140
	v_add_f32_e32 v140, v210, v140
	v_add_f32_e32 v140, v211, v140
	v_add_f32_e32 v140, v237, v140
	v_add_f32_e32 v140, v238, v140
	v_add_f32_e32 v140, v239, v140
	v_add_f32_e32 v140, v240, v140
	v_add_f32_e32 v140, v241, v140
	v_add_f32_e32 v140, v242, v140
	v_add_f32_e32 v140, v243, v140
	v_add_f32_e32 v140, v244, v140
	v_add_f32_e32 v140, v245, v140
	v_add_f32_e32 v235, v246, v140
	v_mov_b32_e32 v236, v235
	v_cvt_pk_bf16_f32 v140, v133, v135
	v_cvt_pk_bf16_f32 v141, v131, v134
	v_cvt_pk_bf16_f32 v142, v130, v132
	v_cvt_pk_bf16_f32 v143, v128, v129
	s_nop 1
	v_permlane32_swap_b32_e32 v235, v236
	v_permlane32_swap_b32_e32 v140, v142
	v_permlane32_swap_b32_e32 v141, v143
	v_cvt_pk_bf16_f32 v144, v125, v127
	v_cvt_pk_bf16_f32 v145, v124, v126
	v_cvt_pk_bf16_f32 v146, v121, v123
	v_cvt_pk_bf16_f32 v147, v120, v122
	v_cvt_pk_bf16_f32 v208, v136, v137
	v_cvt_pk_bf16_f32 v209, v138, v139
	v_cvt_pk_bf16_f32 v210, v210, v211
	v_cvt_pk_bf16_f32 v211, v237, v238
	v_cvt_pk_bf16_f32 v238, v239, v240
	v_cvt_pk_bf16_f32 v239, v241, v242
	v_cvt_pk_bf16_f32 v240, v243, v244
	v_cvt_pk_bf16_f32 v241, v245, v246
	s_nop 0
	v_permlane32_swap_b32_e32 v144, v146
	v_permlane32_swap_b32_e32 v145, v147
	v_permlane32_swap_b32_e32 v208, v210
	v_permlane32_swap_b32_e32 v209, v211
	v_permlane32_swap_b32_e32 v238, v240
	v_permlane32_swap_b32_e32 v239, v241
	s_mov_b32 s4, 0x234c0000
	v_add_co_u32_e32 v120, vcc, s4, v164
	s_mov_b32 s4, 0x234e0000
	s_nop 0
	v_addc_co_u32_e32 v121, vcc, 0, v165, vcc
	v_add_co_u32_e32 v124, vcc, s4, v164
	s_nop 1
	v_addc_co_u32_e32 v125, vcc, 0, v165, vcc
	v_add_co_u32_e32 v128, vcc, s95, v166
	global_load_dwordx4 v[120:123], v[120:121], off
	s_nop 0
	global_load_dwordx4 v[124:127], v[124:125], off
	v_addc_co_u32_e32 v129, vcc, 0, v167, vcc
	v_add_co_u32_e32 v132, vcc, s95, v168
	s_nop 1
	v_addc_co_u32_e32 v133, vcc, 0, v169, vcc
	v_add_co_u32_e32 v136, vcc, s95, v170
	global_load_dwordx4 v[128:131], v[128:129], off
	s_nop 0
	global_load_dwordx4 v[132:135], v[132:133], off
	v_addc_co_u32_e32 v137, vcc, 0, v171, vcc
	global_load_dwordx4 v[136:139], v[136:137], off
	ds_read_b64_tr_b16 v[164:165], v175 offset:0
	ds_read_b64_tr_b16 v[166:167], v175 offset:0x800
	ds_read_b64_tr_b16 v[168:169], v175 offset:0x1000
	ds_read_b64_tr_b16 v[170:171], v175 offset:0x1800
	ds_read_b64_tr_b16 v[242:243], v175 offset:0x2000
	ds_read_b64_tr_b16 v[244:245], v175 offset:0x2800
	ds_read_b64_tr_b16 v[246:247], v175 offset:0x3000
	ds_read_b64_tr_b16 v[248:249], v175 offset:0x3800
	s_waitcnt lgkmcnt(0)
	s_nop 0
	v_mfma_f32_32x32x16_bf16 v[0:15], v[140:143], v[164:167], v[0:15]
	ds_read_b64_tr_b16 v[164:165], v175 offset:0x200
	ds_read_b64_tr_b16 v[166:167], v175 offset:0xa00
	v_mfma_f32_32x32x16_bf16 v[0:15], v[144:147], v[168:171], v[0:15]
	ds_read_b64_tr_b16 v[168:169], v175 offset:0x1200
	ds_read_b64_tr_b16 v[170:171], v175 offset:0x1a00
	v_mfma_f32_32x32x16_bf16 v[0:15], v[208:211], v[242:245], v[0:15]
	ds_read_b64_tr_b16 v[242:243], v175 offset:0x2200
	ds_read_b64_tr_b16 v[244:245], v175 offset:0x2a00
	v_mfma_f32_32x32x16_bf16 v[0:15], v[238:241], v[246:249], v[0:15]
	ds_read_b64_tr_b16 v[246:247], v175 offset:0x3200
	ds_read_b64_tr_b16 v[248:249], v175 offset:0x3a00
	s_waitcnt lgkmcnt(0)
; template <int D0> __device__ __forceinline__ void pv_one(f32x16& od, int vb, bf16x8 pa0, bf16x8 pa1, bf16x8 pa2, bf16x8 pa3) {
;     const s16x4 l0 = tr_read<v_rd_off(D0, 0, 0)>(vb), h0 = tr_read<v_rd_off(D0, 0, 1)>(vb), l1 = tr_read<v_rd_off(D0, 1, 0)>(vb), h1 = tr_read<v_rd_off(D0, 1, 1)>(vb);
;     const s16x4 l2 = tr_read<v_rd_off(D0, 2, 0)>(vb), h2 = tr_read<v_rd_off(D0, 2, 1)>(vb), l3 = tr_read<v_rd_off(D0, 3, 0)>(vb), h3 = tr_read<v_rd_off(D0, 3, 1)>(vb);
;     asm volatile("s_waitcnt lgkmcnt(0)" ::: "memory"); SBAR();
;     ...
;     od = __builtin_amdgcn_mfma_f32_32x32x16_bf16(pa0, PK(l0, h0), od, 0, 0, 0);
;     od = __builtin_amdgcn_mfma_f32_32x32x16_bf16(pa1, PK(l1, h1), od, 0, 0, 0);
;     od = __builtin_amdgcn_mfma_f32_32x32x16_bf16(pa2, PK(l2, h2), od, 0, 0, 0);
;     od = __builtin_amdgcn_mfma_f32_32x32x16_bf16(pa3, PK(l3, h3), od, 0, 0, 0);
;     ...
; }
; __device__ __forceinline__ void pv_d0(f32x16* o, int vb, bf16x8 pa0, bf16x8 pa1, bf16x8 pa2, bf16x8 pa3) {
;     pv_one<0>(o[0], vb, pa0, pa1, pa2, pa3); pv_one<1>(o[1], vb, pa0, pa1, pa2, pa3); pv_one<2>(o[2], vb, pa0, pa1, pa2, pa3); pv_one<3>(o[3], vb, pa0, pa1, pa2, pa3);
; }
; __device__ __forceinline__ void attn_unit(const bf16_t* __restrict__ Qb, const bf16_t* __restrict__ Kh, const bf16_t* __restrict__ Vh, bf16_t* __restrict__ Ob, int seq, char* lds) {
;     ...
;     f32x16 pA0, pA1, pB0, pB1; float mnA, mnB, alA, alB; bf16x8 pa0, pa1, pa2, pa3; const int NT = seq / KVBLK;
;     SLOAD(0); SWAIT(); SWRITE(0); __syncthreads();
;     qkt(pA0, pA1, K_lds, qr, qrl, r32, hi); partialSM(pA0, pA1, m_reg, mnA, alA);
;     SLOAD(KVBLK);
;     SWAIT(); SWRITE(1); __syncthreads();
;     for (int j = 1; j + 1 < NT; j += 2) {
;         SBAR(); qkt(pB0, pB1, K_lds + SHM_K, qr, qrl, r32, hi);
;         finishSM(pA0, pA1, alA, l_reg, pa0, pa1, pa2, pa3); SBAR();
;         SLOAD((j + 1) * KVBLK); SBAR();
;         pv_d0(o, vb0, pa0, pa1, pa2, pa3); partialSM(pB0, pB1, m_reg, mnB, alB);
;         __syncthreads(); SWAIT(); SWRITE(0);
;         RESC(alB); __syncthreads();
;         SBAR(); qkt(pA0, pA1, K_lds, qr, qrl, r32, hi);
;         finishSM(pB0, pB1, alB, l_reg, pa0, pa1, pa2, pa3); SBAR();
;         SLOAD((j + 2) * KVBLK); SBAR();
;         pv_d0(o, vb0 + SHM_V, pa0, pa1, pa2, pa3); partialSM(pA0, pA1, m_reg, mnA, alA);
;         __syncthreads(); SWAIT(); SWRITE(1);
;         RESC(alA); __syncthreads();
	v_mfma_f32_32x32x16_bf16 v[48:63], v[140:143], v[164:167], v[48:63]
	ds_read_b64_tr_b16 v[164:165], v175 offset:0x400
	ds_read_b64_tr_b16 v[166:167], v175 offset:0xc00
	v_mfma_f32_32x32x16_bf16 v[48:63], v[144:147], v[168:171], v[48:63]
	ds_read_b64_tr_b16 v[168:169], v175 offset:0x1400
	ds_read_b64_tr_b16 v[170:171], v175 offset:0x1c00
	v_mfma_f32_32x32x16_bf16 v[48:63], v[208:211], v[242:245], v[48:63]
	ds_read_b64_tr_b16 v[242:243], v175 offset:0x2400
	ds_read_b64_tr_b16 v[244:245], v175 offset:0x2c00
	v_mfma_f32_32x32x16_bf16 v[48:63], v[238:241], v[246:249], v[48:63]
	ds_read_b64_tr_b16 v[246:247], v175 offset:0x3400
	ds_read_b64_tr_b16 v[248:249], v175 offset:0x3c00
	s_waitcnt lgkmcnt(0)
	v_mfma_f32_32x32x16_bf16 v[32:47], v[140:143], v[164:167], v[32:47]
	ds_read_b64_tr_b16 v[164:165], v175 offset:0x600
	ds_read_b64_tr_b16 v[166:167], v175 offset:0xe00
	v_mfma_f32_32x32x16_bf16 v[32:47], v[144:147], v[168:171], v[32:47]
	ds_read_b64_tr_b16 v[168:169], v175 offset:0x1600
	ds_read_b64_tr_b16 v[170:171], v175 offset:0x1e00
	v_mfma_f32_32x32x16_bf16 v[32:47], v[208:211], v[242:245], v[32:47]
	ds_read_b64_tr_b16 v[242:243], v175 offset:0x2600
	ds_read_b64_tr_b16 v[244:245], v175 offset:0x2e00
	v_mfma_f32_32x32x16_bf16 v[32:47], v[238:241], v[246:249], v[32:47]
	ds_read_b64_tr_b16 v[246:247], v175 offset:0x3600
	ds_read_b64_tr_b16 v[248:249], v175 offset:0x3e00
	s_waitcnt lgkmcnt(0)
	v_mfma_f32_32x32x16_bf16 v[16:31], v[140:143], v[164:167], v[16:31]
	v_max_f32_e32 v140, v81, v81
	v_max_f32_e32 v141, v80, v80
	v_max_f32_e32 v140, v141, v140
	v_max3_f32 v140, v140, v82, v83
	v_max3_f32 v140, v140, v84, v85
	v_max3_f32 v140, v140, v86, v87
	v_max3_f32 v140, v140, v88, v89
	v_max3_f32 v140, v140, v90, v91
	v_mfma_f32_32x32x16_bf16 v[16:31], v[144:147], v[168:171], v[16:31]
	v_max3_f32 v140, v140, v92, v93
	v_max3_f32 v140, v140, v94, v95
	v_max3_f32 v140, v140, v64, v65
	v_max3_f32 v140, v140, v66, v67
	v_max3_f32 v140, v140, v68, v69
	v_max3_f32 v140, v140, v70, v71
	v_max3_f32 v140, v140, v72, v73
	v_max3_f32 v140, v140, v74, v75
	v_mfma_f32_32x32x16_bf16 v[16:31], v[208:211], v[242:245], v[16:31]
	v_max3_f32 v140, v140, v76, v77
	v_max3_f32 v140, v140, v78, v79
	v_mov_b32_e32 v141, v140
	s_nop 1
	v_permlane32_swap_b32_e32 v140, v141
	v_max_f32_e32 v141, v141, v141
	v_max_f32_e32 v140, v140, v140
	v_max_f32_e32 v140, v140, v141
	v_sub_f32_e32 v141, v140, v158
	v_cmp_ge_f32_e32 vcc, s62, v141
	v_max_f32_e32 v141, v158, v158
	v_mfma_f32_32x32x16_bf16 v[16:31], v[238:241], v[246:249], v[16:31]
	v_max_f32_e32 v141, v141, v140
	v_sub_f32_e32 v140, v158, v141
	v_exp_f32_e32 v140, v140
	s_cmp_eq_u64 vcc, exec
	s_cselect_b64 s[4:5], -1, 0
	s_barrier
	v_cndmask_b32_e64 v140, v140, 1.0, s[4:5]
	v_cmp_gt_f32_e32 vcc, 1.0, v140
	s_waitcnt vmcnt(4)
	ds_write_b128 v178, v[120:123] offset:16384
	s_waitcnt vmcnt(3)
	ds_write_b128 v179, v[124:127] offset:16384
	s_waitcnt vmcnt(2)
	ds_write_b128 v216, v[128:131]
	s_waitcnt vmcnt(1)
	ds_write_b128 v217, v[132:135]
	s_waitcnt vmcnt(0)
	ds_write_b128 v218, v[136:139]
	s_cbranch_vccz .LBB0_1388
	s_and_saveexec_b64 s[12:13], s[2:3]
	ds_write_b32 v173, v140 offset:128
	s_or_b64 exec, exec, s[12:13]
	s_waitcnt lgkmcnt(0)
	v_add_u32_e32 v132, v149, v160
	ds_read_b128 v[120:123], v132 offset:224
	ds_read_b128 v[124:127], v132 offset:192
	ds_read_b128 v[128:131], v132 offset:160
	ds_read_b128 v[132:135], v132 offset:128
	s_waitcnt lgkmcnt(3)
	v_pk_mul_f32 v[12:13], v[12:13], v[120:121]
	s_waitcnt lgkmcnt(2)
	v_pk_mul_f32 v[8:9], v[8:9], v[124:125]
	s_waitcnt lgkmcnt(1)
	v_pk_mul_f32 v[4:5], v[4:5], v[128:129]
	v_pk_mul_f32 v[14:15], v[14:15], v[122:123]
	v_pk_mul_f32 v[10:11], v[10:11], v[126:127]
	v_pk_mul_f32 v[6:7], v[6:7], v[130:131]
	s_waitcnt lgkmcnt(0)
	v_pk_mul_f32 v[2:3], v[2:3], v[134:135]
	v_pk_mul_f32 v[0:1], v[0:1], v[132:133]
	v_pk_mul_f32 v[60:61], v[60:61], v[120:121]
	v_pk_mul_f32 v[56:57], v[56:57], v[124:125]
	v_pk_mul_f32 v[52:53], v[52:53], v[128:129]
	v_pk_mul_f32 v[62:63], v[62:63], v[122:123]
	v_pk_mul_f32 v[58:59], v[58:59], v[126:127]
	v_pk_mul_f32 v[54:55], v[54:55], v[130:131]
	v_pk_mul_f32 v[50:51], v[50:51], v[134:135]
	v_pk_mul_f32 v[48:49], v[48:49], v[132:133]
	v_pk_mul_f32 v[44:45], v[44:45], v[120:121]
	v_pk_mul_f32 v[40:41], v[40:41], v[124:125]
	v_pk_mul_f32 v[36:37], v[36:37], v[128:129]
	v_pk_mul_f32 v[46:47], v[46:47], v[122:123]
	v_pk_mul_f32 v[42:43], v[42:43], v[126:127]
	v_pk_mul_f32 v[38:39], v[38:39], v[130:131]
	v_pk_mul_f32 v[34:35], v[34:35], v[134:135]
	v_pk_mul_f32 v[32:33], v[32:33], v[132:133]
	v_pk_mul_f32 v[28:29], v[28:29], v[120:121]
	v_pk_mul_f32 v[24:25], v[24:25], v[124:125]
	v_pk_mul_f32 v[20:21], v[20:21], v[128:129]
	v_pk_mul_f32 v[30:31], v[30:31], v[122:123]
	v_pk_mul_f32 v[26:27], v[26:27], v[126:127]
	v_pk_mul_f32 v[22:23], v[22:23], v[130:131]
	v_pk_mul_f32 v[18:19], v[18:19], v[134:135]
	v_pk_mul_f32 v[16:17], v[16:17], v[132:133]
